# FFN-down tail as a 2-way split-K round on 128 workgroups (40/48 K-tiles, one third of the partial traffic) instead of 4-way on 256
# baseline (speedup 1.0000x reference)
.LBB0_1276:
	s_and_b64 vcc, exec, s[74:75]
	s_cbranch_vccz .LBB0_1279
	s_cmp_lt_i32 s54, 5
	s_cbranch_scc0 .LBB0_1279
	s_add_i32 s4, s54, s91
	s_mul_i32 s4, s4, s3
	s_add_i32 s77, s4, s89
	s_cmp_eq_u32 s54, 4
	s_cbranch_scc0 .Lsk_nt1
	s_lshr_b32 s5, s1, 3
	s_cmp_lt_u32 s5, 16
	s_cbranch_scc1 .Lsk_part
	s_mov_b64 s[4:5], 0
	s_branch .LBB0_1279
.Lsk_part:
	s_and_b32 s4, s1, 7
	s_lshl_b32 s4, s4, 4
	s_add_i32 s4, s4, s5
	s_lshr_b32 s4, s4, 1
	s_add_i32 s77, s4, 0x80
	s_cmp_ge_u32 s4, 32
	s_cselect_b32 s4, 0x80, 0
	s_add_i32 s77, s77, s4

.LBB0_1285:
	s_cmp_eq_u32 s54, 4
	s_cbranch_scc0 .Lsk_nt2
	s_bfe_u32 s67, s1, 0x10003
	s_mulk_i32 s67, 0x1400
	s_add_u32 s74, s74, s67
	s_addc_u32 s75, s75, 0
	s_add_u32 s76, s76, s67
	s_addc_u32 s77, s77, 0

.LBB0_1289:
	s_lshl_b32 s80, s96, 8
	s_ashr_i32 s81, s80, 31
	s_lshl_b64 s[86:87], s[80:81], 2
	s_add_u32 s84, s84, s86
	s_addc_u32 s85, s85, s87
	s_add_i32 m0, s94, s41
	s_add_u32 s81, s82, 0x100
	global_load_lds_dwordx4 v239, s[84:85]
	s_addc_u32 s96, s83, 0
	s_cmp_eq_u32 s54, 5
	s_cselect_b32 vcc_lo, 46, -2
	s_bfe_u32 s86, s1, 0x10003
	s_cmp_eq_u32 s86, 1
	s_cselect_b32 s86, -8, 0
	s_cmp_eq_u32 s54, 5
	s_cselect_b32 s86, s86, 0
	s_add_i32 vcc_lo, vcc_lo, s86
	s_add_u32 s82, s78, 0x100
	s_addc_u32 s83, s79, 0
	s_add_i32 s94, 0, 0x10000
	s_cmpk_eq_i32 vcc_lo, 0x54
	s_cselect_b32 s87, s75, s83
	s_cselect_b32 s86, s74, s82
	s_cselect_b32 s85, s77, s96
	s_cselect_b32 s84, s76, s81
	s_add_i32 vcc_hi, 0, 0x14000
	s_add_i32 m0, s29, 0xc000
	global_load_lds_dwordx4 v230, s[78:79]
	s_add_i32 m0, s29, 0xe000
	s_nop 0
	global_load_lds_dwordx4 v232, s[78:79]
	s_waitcnt vmcnt(8)
	s_waitcnt lgkmcnt(0)
	s_barrier
	s_waitcnt lgkmcnt(0)
	v_mfma_f32_16x16x32_bf16 v[176:179], v[64:67], v[152:155], 0
	v_mfma_f32_16x16x32_bf16 v[176:179], v[72:75], v[156:159], v[176:179]
	v_mfma_f32_16x16x32_bf16 v[148:151], v[108:111], v[152:155], 0
	v_mfma_f32_16x16x32_bf16 v[148:151], v[116:119], v[156:159], v[148:151]
	v_mfma_f32_16x16x32_bf16 v[172:175], v[88:91], v[152:155], 0
	v_mfma_f32_16x16x32_bf16 v[172:175], v[96:99], v[156:159], v[172:175]
	v_mfma_f32_16x16x32_bf16 v[144:147], v[128:131], v[152:155], 0
	v_mfma_f32_16x16x32_bf16 v[144:147], v[140:143], v[156:159], v[144:147]
	v_mfma_f32_16x16x32_bf16 v[136:139], v[64:67], v[160:163], 0
	v_mfma_f32_16x16x32_bf16 v[136:139], v[72:75], v[164:167], v[136:139]
	v_mfma_f32_16x16x32_bf16 v[124:127], v[108:111], v[160:163], 0
	v_mfma_f32_16x16x32_bf16 v[124:127], v[116:119], v[164:167], v[124:127]
	v_mfma_f32_16x16x32_bf16 v[132:135], v[88:91], v[160:163], 0
	v_mfma_f32_16x16x32_bf16 v[132:135], v[96:99], v[164:167], v[132:135]
	v_mfma_f32_16x16x32_bf16 v[120:123], v[128:131], v[160:163], 0
	v_mfma_f32_16x16x32_bf16 v[120:123], v[140:143], v[164:167], v[120:123]
	v_mfma_f32_16x16x32_bf16 v[112:115], v[64:67], v[168:171], 0
	v_mfma_f32_16x16x32_bf16 v[112:115], v[72:75], v[180:183], v[112:115]
	v_mfma_f32_16x16x32_bf16 v[100:103], v[108:111], v[168:171], 0
	v_mfma_f32_16x16x32_bf16 v[100:103], v[116:119], v[180:183], v[100:103]
	v_mfma_f32_16x16x32_bf16 v[104:107], v[88:91], v[168:171], 0
	v_mfma_f32_16x16x32_bf16 v[104:107], v[96:99], v[180:183], v[104:107]
	v_mfma_f32_16x16x32_bf16 v[92:95], v[128:131], v[168:171], 0
	v_mfma_f32_16x16x32_bf16 v[92:95], v[140:143], v[180:183], v[92:95]
	v_mfma_f32_16x16x32_bf16 v[84:87], v[64:67], v[184:187], 0
	v_mfma_f32_16x16x32_bf16 v[84:87], v[72:75], v[188:191], v[84:87]
	v_mfma_f32_16x16x32_bf16 v[76:79], v[108:111], v[184:187], 0
	v_mfma_f32_16x16x32_bf16 v[76:79], v[116:119], v[188:191], v[76:79]
	v_mfma_f32_16x16x32_bf16 v[80:83], v[88:91], v[184:187], 0
	v_mfma_f32_16x16x32_bf16 v[80:83], v[96:99], v[188:191], v[80:83]
	v_mfma_f32_16x16x32_bf16 v[68:71], v[128:131], v[184:187], 0
	v_mfma_f32_16x16x32_bf16 v[68:71], v[140:143], v[188:191], v[68:71]
	s_barrier
	s_add_i32 s78, s94, s2
	s_mov_b32 m0, s78
	ds_read_b128 v[152:155], v240 offset:16384
	ds_read_b128 v[156:159], v240 offset:17408
	ds_read_b128 v[160:163], v240 offset:18432
	ds_read_b128 v[164:167], v240 offset:19456
	ds_read_b128 v[168:171], v240 offset:20480
	ds_read_b128 v[180:183], v240 offset:21504
	ds_read_b128 v[184:187], v240 offset:22528
	ds_read_b128 v[188:191], v240 offset:23552
	global_load_lds_dwordx4 v216, s[84:85]
	s_add_i32 m0, s78, 0x2000
	s_add_u32 s78, s84, 0x160000
	s_addc_u32 s79, s85, 0
	s_add_i32 s94, vcc_hi, s2
	global_load_lds_dwordx4 v228, s[84:85]
	s_mov_b32 m0, s94
	s_nop 0
	global_load_lds_dwordx4 v216, s[78:79]
	s_add_i32 m0, s94, 0x2000
	s_nop 0
	global_load_lds_dwordx4 v228, s[78:79]
	s_mov_b32 m0, s29
	s_nop 0
	global_load_lds_dwordx4 v224, s[86:87]
	s_mov_b32 m0, s34
	s_nop 0
	global_load_lds_dwordx4 v226, s[86:87]
	s_waitcnt vmcnt(8)
	s_waitcnt lgkmcnt(0)
	s_barrier
	s_waitcnt lgkmcnt(0)
	v_mfma_f32_16x16x32_bf16 v[60:63], v[64:67], v[152:155], 0
	v_mfma_f32_16x16x32_bf16 v[60:63], v[72:75], v[156:159], v[60:63]
	v_mfma_f32_16x16x32_bf16 v[52:55], v[108:111], v[152:155], 0
	v_mfma_f32_16x16x32_bf16 v[52:55], v[116:119], v[156:159], v[52:55]
	v_mfma_f32_16x16x32_bf16 v[56:59], v[88:91], v[152:155], 0
	v_mfma_f32_16x16x32_bf16 v[56:59], v[96:99], v[156:159], v[56:59]
	v_mfma_f32_16x16x32_bf16 v[48:51], v[128:131], v[152:155], 0
	v_mfma_f32_16x16x32_bf16 v[48:51], v[140:143], v[156:159], v[48:51]
	v_mfma_f32_16x16x32_bf16 v[44:47], v[64:67], v[160:163], 0
	v_mfma_f32_16x16x32_bf16 v[44:47], v[72:75], v[164:167], v[44:47]
	v_mfma_f32_16x16x32_bf16 v[36:39], v[108:111], v[160:163], 0
	v_mfma_f32_16x16x32_bf16 v[36:39], v[116:119], v[164:167], v[36:39]
	v_mfma_f32_16x16x32_bf16 v[40:43], v[88:91], v[160:163], 0
	v_mfma_f32_16x16x32_bf16 v[40:43], v[96:99], v[164:167], v[40:43]
	v_mfma_f32_16x16x32_bf16 v[32:35], v[128:131], v[160:163], 0
	v_mfma_f32_16x16x32_bf16 v[32:35], v[140:143], v[164:167], v[32:35]
	v_mfma_f32_16x16x32_bf16 v[28:31], v[64:67], v[168:171], 0
	v_mfma_f32_16x16x32_bf16 v[28:31], v[72:75], v[180:183], v[28:31]
	v_mfma_f32_16x16x32_bf16 v[20:23], v[108:111], v[168:171], 0
	v_mfma_f32_16x16x32_bf16 v[20:23], v[116:119], v[180:183], v[20:23]
	v_mfma_f32_16x16x32_bf16 v[24:27], v[88:91], v[168:171], 0
	v_mfma_f32_16x16x32_bf16 v[24:27], v[96:99], v[180:183], v[24:27]
	v_mfma_f32_16x16x32_bf16 v[16:19], v[128:131], v[168:171], 0
	v_mfma_f32_16x16x32_bf16 v[16:19], v[140:143], v[180:183], v[16:19]
	v_mfma_f32_16x16x32_bf16 v[12:15], v[64:67], v[184:187], 0
	v_mfma_f32_16x16x32_bf16 v[12:15], v[72:75], v[188:191], v[12:15]
	v_mfma_f32_16x16x32_bf16 v[4:7], v[108:111], v[184:187], 0
	v_mfma_f32_16x16x32_bf16 v[4:7], v[116:119], v[188:191], v[4:7]
	v_mfma_f32_16x16x32_bf16 v[8:11], v[88:91], v[184:187], 0
	v_mfma_f32_16x16x32_bf16 v[8:11], v[96:99], v[188:191], v[8:11]
	v_mfma_f32_16x16x32_bf16 v[0:3], v[128:131], v[184:187], 0
	v_mfma_f32_16x16x32_bf16 v[0:3], v[140:143], v[188:191], v[0:3]
	s_barrier
	s_add_i32 s94, 0, 0x18000
	s_add_i32 vcc_hi, 0, 0x1c000
	ds_read_b128 v[64:67], v192 offset:32768
	ds_read_b128 v[72:75], v192 offset:33792
	ds_read_b128 v[88:91], v192 offset:34816
	ds_read_b128 v[96:99], v192 offset:35840
	ds_read_b128 v[108:111], v192 offset:49152
	ds_read_b128 v[116:119], v192 offset:50176
	ds_read_b128 v[128:131], v192 offset:51200
	ds_read_b128 v[140:143], v192 offset:52224
	s_add_u32 s78, s86, 0x160000
	s_addc_u32 s79, s87, 0
	s_mov_b32 m0, s35
	ds_read_b128 v[152:155], v240 offset:32768
	ds_read_b128 v[156:159], v240 offset:33792
	ds_read_b128 v[160:163], v240 offset:34816
	ds_read_b128 v[164:167], v240 offset:35840
	ds_read_b128 v[168:171], v240 offset:36864
	ds_read_b128 v[180:183], v240 offset:37888
	ds_read_b128 v[184:187], v240 offset:38912
	ds_read_b128 v[188:191], v240 offset:39936
	global_load_lds_dwordx4 v224, s[78:79]
	s_mov_b32 m0, s38
	s_nop 0
	global_load_lds_dwordx4 v226, s[78:79]
	s_waitcnt vmcnt(8)
	s_waitcnt lgkmcnt(0)
	s_barrier
	s_waitcnt lgkmcnt(0)
	v_mfma_f32_16x16x32_bf16 v[176:179], v[64:67], v[152:155], v[176:179]
	v_mfma_f32_16x16x32_bf16 v[176:179], v[72:75], v[156:159], v[176:179]
	v_mfma_f32_16x16x32_bf16 v[148:151], v[108:111], v[152:155], v[148:151]
	v_mfma_f32_16x16x32_bf16 v[148:151], v[116:119], v[156:159], v[148:151]
	v_mfma_f32_16x16x32_bf16 v[172:175], v[88:91], v[152:155], v[172:175]
	v_mfma_f32_16x16x32_bf16 v[172:175], v[96:99], v[156:159], v[172:175]
	v_mfma_f32_16x16x32_bf16 v[144:147], v[128:131], v[152:155], v[144:147]
	v_mfma_f32_16x16x32_bf16 v[144:147], v[140:143], v[156:159], v[144:147]
	v_mfma_f32_16x16x32_bf16 v[136:139], v[64:67], v[160:163], v[136:139]
	v_mfma_f32_16x16x32_bf16 v[136:139], v[72:75], v[164:167], v[136:139]
	v_mfma_f32_16x16x32_bf16 v[124:127], v[108:111], v[160:163], v[124:127]
	v_mfma_f32_16x16x32_bf16 v[124:127], v[116:119], v[164:167], v[124:127]
	v_mfma_f32_16x16x32_bf16 v[132:135], v[88:91], v[160:163], v[132:135]
	v_mfma_f32_16x16x32_bf16 v[132:135], v[96:99], v[164:167], v[132:135]
	v_mfma_f32_16x16x32_bf16 v[120:123], v[128:131], v[160:163], v[120:123]
	v_mfma_f32_16x16x32_bf16 v[120:123], v[140:143], v[164:167], v[120:123]
	v_mfma_f32_16x16x32_bf16 v[112:115], v[64:67], v[168:171], v[112:115]
	v_mfma_f32_16x16x32_bf16 v[112:115], v[72:75], v[180:183], v[112:115]
	v_mfma_f32_16x16x32_bf16 v[100:103], v[108:111], v[168:171], v[100:103]
	v_mfma_f32_16x16x32_bf16 v[100:103], v[116:119], v[180:183], v[100:103]
	v_mfma_f32_16x16x32_bf16 v[104:107], v[88:91], v[168:171], v[104:107]
	v_mfma_f32_16x16x32_bf16 v[104:107], v[96:99], v[180:183], v[104:107]
	v_mfma_f32_16x16x32_bf16 v[92:95], v[128:131], v[168:171], v[92:95]
	v_mfma_f32_16x16x32_bf16 v[92:95], v[140:143], v[180:183], v[92:95]
	v_mfma_f32_16x16x32_bf16 v[84:87], v[64:67], v[184:187], v[84:87]
	v_mfma_f32_16x16x32_bf16 v[84:87], v[72:75], v[188:191], v[84:87]
	v_mfma_f32_16x16x32_bf16 v[76:79], v[108:111], v[184:187], v[76:79]
	v_mfma_f32_16x16x32_bf16 v[76:79], v[116:119], v[188:191], v[76:79]
	v_mfma_f32_16x16x32_bf16 v[80:83], v[88:91], v[184:187], v[80:83]
	v_mfma_f32_16x16x32_bf16 v[80:83], v[96:99], v[188:191], v[80:83]
	v_mfma_f32_16x16x32_bf16 v[68:71], v[128:131], v[184:187], v[68:71]
	v_mfma_f32_16x16x32_bf16 v[68:71], v[140:143], v[188:191], v[68:71]
	s_barrier
	s_add_i32 s78, s94, s2
	s_add_u32 s98, s84, 0x80
	s_addc_u32 s99, s85, 0
	s_mov_b32 m0, s78
	ds_read_b128 v[152:155], v240 offset:49152
	ds_read_b128 v[156:159], v240 offset:50176
	ds_read_b128 v[160:163], v240 offset:51200
	ds_read_b128 v[164:167], v240 offset:52224
	ds_read_b128 v[168:171], v240 offset:53248
	ds_read_b128 v[180:183], v240 offset:54272
	ds_read_b128 v[184:187], v240 offset:55296
	ds_read_b128 v[188:191], v240 offset:56320
	global_load_lds_dwordx4 v216, s[98:99]
	s_add_i32 m0, s78, 0x2000
	s_add_u32 s78, s84, 0x160080
	s_addc_u32 s79, s85, 0
	s_add_i32 s84, vcc_hi, s2
	global_load_lds_dwordx4 v228, s[98:99]
	s_mov_b32 m0, s84
	s_nop 0
	global_load_lds_dwordx4 v216, s[78:79]
	s_add_i32 m0, s84, 0x2000
	s_nop 0
	global_load_lds_dwordx4 v228, s[78:79]
	s_add_u32 s98, s86, 0x80
	s_addc_u32 s99, s87, 0
	s_mov_b32 m0, s60
	s_nop 0
	global_load_lds_dwordx4 v224, s[98:99]
	s_mov_b32 m0, s61
	s_nop 0
	global_load_lds_dwordx4 v226, s[98:99]
	s_waitcnt vmcnt(8)
	s_waitcnt lgkmcnt(0)
	s_barrier
	s_waitcnt lgkmcnt(0)
	v_mfma_f32_16x16x32_bf16 v[60:63], v[64:67], v[152:155], v[60:63]
	v_mfma_f32_16x16x32_bf16 v[60:63], v[72:75], v[156:159], v[60:63]
	v_mfma_f32_16x16x32_bf16 v[52:55], v[108:111], v[152:155], v[52:55]
	v_mfma_f32_16x16x32_bf16 v[52:55], v[116:119], v[156:159], v[52:55]
	v_mfma_f32_16x16x32_bf16 v[56:59], v[88:91], v[152:155], v[56:59]
	v_mfma_f32_16x16x32_bf16 v[56:59], v[96:99], v[156:159], v[56:59]
	v_mfma_f32_16x16x32_bf16 v[48:51], v[128:131], v[152:155], v[48:51]
	v_mfma_f32_16x16x32_bf16 v[48:51], v[140:143], v[156:159], v[48:51]
	v_mfma_f32_16x16x32_bf16 v[44:47], v[64:67], v[160:163], v[44:47]
	v_mfma_f32_16x16x32_bf16 v[44:47], v[72:75], v[164:167], v[44:47]
	v_mfma_f32_16x16x32_bf16 v[36:39], v[108:111], v[160:163], v[36:39]
	v_mfma_f32_16x16x32_bf16 v[36:39], v[116:119], v[164:167], v[36:39]
	v_mfma_f32_16x16x32_bf16 v[40:43], v[88:91], v[160:163], v[40:43]
	v_mfma_f32_16x16x32_bf16 v[40:43], v[96:99], v[164:167], v[40:43]
	v_mfma_f32_16x16x32_bf16 v[32:35], v[128:131], v[160:163], v[32:35]
	v_mfma_f32_16x16x32_bf16 v[32:35], v[140:143], v[164:167], v[32:35]
	v_mfma_f32_16x16x32_bf16 v[28:31], v[64:67], v[168:171], v[28:31]
	v_mfma_f32_16x16x32_bf16 v[28:31], v[72:75], v[180:183], v[28:31]
	v_mfma_f32_16x16x32_bf16 v[20:23], v[108:111], v[168:171], v[20:23]
	v_mfma_f32_16x16x32_bf16 v[20:23], v[116:119], v[180:183], v[20:23]
	v_mfma_f32_16x16x32_bf16 v[24:27], v[88:91], v[168:171], v[24:27]
	v_mfma_f32_16x16x32_bf16 v[24:27], v[96:99], v[180:183], v[24:27]
	v_mfma_f32_16x16x32_bf16 v[16:19], v[128:131], v[168:171], v[16:19]
	v_mfma_f32_16x16x32_bf16 v[16:19], v[140:143], v[180:183], v[16:19]
	v_mfma_f32_16x16x32_bf16 v[12:15], v[64:67], v[184:187], v[12:15]
	v_mfma_f32_16x16x32_bf16 v[12:15], v[72:75], v[188:191], v[12:15]
	v_mfma_f32_16x16x32_bf16 v[4:7], v[108:111], v[184:187], v[4:7]
	v_mfma_f32_16x16x32_bf16 v[4:7], v[116:119], v[188:191], v[4:7]
	v_mfma_f32_16x16x32_bf16 v[8:11], v[88:91], v[184:187], v[8:11]
	v_mfma_f32_16x16x32_bf16 v[8:11], v[96:99], v[188:191], v[8:11]
	v_mfma_f32_16x16x32_bf16 v[0:3], v[128:131], v[184:187], v[0:3]
	v_mfma_f32_16x16x32_bf16 v[0:3], v[140:143], v[188:191], v[0:3]
	s_barrier
	s_add_i32 vcc_lo, vcc_lo, 2
	s_add_u32 s81, s81, 0x100
	s_addc_u32 s96, s96, 0
	s_mov_b64 s[78:79], s[82:83]

.LBB0_1293:
	s_cmp_eq_u32 s54, 5
	s_cbranch_scc0 .Lsk_epi
	v_readlane_b32 s78, v255, 5
	v_readlane_b32 s79, v255, 22
	v_mbcnt_lo_u32_b32 v192, -1, 0
	v_mbcnt_hi_u32_b32 v192, -1, v192
	v_lshlrev_b32_e32 v192, 4, v192
	s_lshr_b32 s78, s78, 6
	s_and_b32 s81, s1, 7
	s_lshl_b32 s81, s81, 4
	s_lshr_b32 s96, s1, 3
	s_add_i32 s81, s81, s96
	s_and_b32 s96, s96, 1
	s_lshr_b32 s81, s81, 1
	s_lshl_b32 s79, s79, 6
	s_add_i32 s79, s79, s81
	s_lshl_b32 s79, s79, 3
	s_add_i32 s79, s79, s78
	s_lshl_b32 s79, s79, 2
	s_add_u32 s98, s14, s79
	s_addc_u32 s99, s15, 0
	s_sub_u32 s98, s98, 0x39580000
	s_subb_u32 s99, s99, 0
	s_lshl_b32 s81, s81, 3
	s_add_i32 s81, s81, s78
	s_lshl_b32 s81, s81, 15
	s_add_u32 s82, s14, s81
	s_addc_u32 s83, s15, 0
	s_sub_u32 s82, s82, 0x19800000
	s_subb_u32 s83, s83, 0
	s_cmp_eq_u32 s96, 1
	s_cbranch_scc1 .Lsk_fin
	s_lshl_b32 s96, s96, 18
	s_add_u32 s82, s82, s96
	s_addc_u32 s83, s83, 0
	global_store_dwordx4 v192, v[0:3], s[82:83] sc1
	global_store_dwordx4 v192, v[4:7], s[82:83] offset:1024 sc1
	global_store_dwordx4 v192, v[8:11], s[82:83] offset:2048 sc1
	global_store_dwordx4 v192, v[12:15], s[82:83] offset:3072 sc1
	s_add_u32 s78, s82, 0x1000
	s_addc_u32 s79, s83, 0
	global_store_dwordx4 v192, v[16:19], s[78:79] sc1
	global_store_dwordx4 v192, v[20:23], s[78:79] offset:1024 sc1
	global_store_dwordx4 v192, v[24:27], s[78:79] offset:2048 sc1
	global_store_dwordx4 v192, v[28:31], s[78:79] offset:3072 sc1
	s_add_u32 s78, s82, 0x2000
	s_addc_u32 s79, s83, 0
	global_store_dwordx4 v192, v[32:35], s[78:79] sc1
	global_store_dwordx4 v192, v[36:39], s[78:79] offset:1024 sc1
	global_store_dwordx4 v192, v[40:43], s[78:79] offset:2048 sc1
	global_store_dwordx4 v192, v[44:47], s[78:79] offset:3072 sc1
	s_add_u32 s78, s82, 0x3000
	s_addc_u32 s79, s83, 0
	global_store_dwordx4 v192, v[48:51], s[78:79] sc1
	global_store_dwordx4 v192, v[52:55], s[78:79] offset:1024 sc1
	global_store_dwordx4 v192, v[56:59], s[78:79] offset:2048 sc1
	global_store_dwordx4 v192, v[60:63], s[78:79] offset:3072 sc1
	s_add_u32 s78, s82, 0x4000
	s_addc_u32 s79, s83, 0
	global_store_dwordx4 v192, v[68:71], s[78:79] sc1
	global_store_dwordx4 v192, v[76:79], s[78:79] offset:1024 sc1
	global_store_dwordx4 v192, v[80:83], s[78:79] offset:2048 sc1
	global_store_dwordx4 v192, v[84:87], s[78:79] offset:3072 sc1
	s_add_u32 s78, s82, 0x5000
	s_addc_u32 s79, s83, 0
	global_store_dwordx4 v192, v[92:95], s[78:79] sc1
	global_store_dwordx4 v192, v[100:103], s[78:79] offset:1024 sc1
	global_store_dwordx4 v192, v[104:107], s[78:79] offset:2048 sc1
	global_store_dwordx4 v192, v[112:115], s[78:79] offset:3072 sc1
	s_add_u32 s78, s82, 0x6000
	s_addc_u32 s79, s83, 0
	global_store_dwordx4 v192, v[120:123], s[78:79] sc1
	global_store_dwordx4 v192, v[124:127], s[78:79] offset:1024 sc1
	global_store_dwordx4 v192, v[132:135], s[78:79] offset:2048 sc1
	global_store_dwordx4 v192, v[136:139], s[78:79] offset:3072 sc1
	s_add_u32 s78, s82, 0x7000
	s_addc_u32 s79, s83, 0
	global_store_dwordx4 v192, v[144:147], s[78:79] sc1
	global_store_dwordx4 v192, v[148:151], s[78:79] offset:1024 sc1
	global_store_dwordx4 v192, v[172:175], s[78:79] offset:2048 sc1
	global_store_dwordx4 v192, v[176:179], s[78:79] offset:3072 sc1
	s_waitcnt vmcnt(0)
	v_mov_b32_e32 v193, 1
	s_mov_b64 exec, 1
	global_atomic_add v217, v193, s[98:99]
	s_mov_b64 exec, -1
	s_branch .Lsk_after_epi

.Lsk_spin:
	global_load_dword v193, v217, s[98:99] sc1
	s_waitcnt vmcnt(0)
	v_readfirstlane_b32 s32, v193
	s_cmp_ge_u32 s32, 1
	s_cbranch_scc1 .Lsk_ready
	s_sleep 2
	s_add_i32 s96, s96, 1
	s_cmp_lt_u32 s96, 0x40000
	s_cbranch_scc1 .Lsk_spin
.Lsk_ready:
	global_load_dwordx4 v[64:67], v192, s[82:83] sc1
	global_load_dwordx4 v[72:75], v192, s[82:83] offset:1024 sc1
	global_load_dwordx4 v[88:91], v192, s[82:83] offset:2048 sc1
	global_load_dwordx4 v[96:99], v192, s[82:83] offset:3072 sc1
	s_add_u32 s78, s82, 0x1000
	s_addc_u32 s79, s83, 0
	global_load_dwordx4 v[108:111], v192, s[78:79] sc1
	global_load_dwordx4 v[116:119], v192, s[78:79] offset:1024 sc1
	global_load_dwordx4 v[128:131], v192, s[78:79] offset:2048 sc1
	global_load_dwordx4 v[140:143], v192, s[78:79] offset:3072 sc1
	s_add_u32 s78, s82, 0x2000
	s_addc_u32 s79, s83, 0
	global_load_dwordx4 v[152:155], v192, s[78:79] sc1
	global_load_dwordx4 v[156:159], v192, s[78:79] offset:1024 sc1
	global_load_dwordx4 v[160:163], v192, s[78:79] offset:2048 sc1
	global_load_dwordx4 v[164:167], v192, s[78:79] offset:3072 sc1
	s_add_u32 s78, s82, 0x3000
	s_addc_u32 s79, s83, 0
	global_load_dwordx4 v[168:171], v192, s[78:79] sc1
	global_load_dwordx4 v[180:183], v192, s[78:79] offset:1024 sc1
	global_load_dwordx4 v[184:187], v192, s[78:79] offset:2048 sc1
	global_load_dwordx4 v[188:191], v192, s[78:79] offset:3072 sc1
	s_add_u32 s78, s82, 0x4000
	s_addc_u32 s79, s83, 0
	global_load_dwordx4 v[194:197], v192, s[78:79] sc1
	global_load_dwordx4 v[198:201], v192, s[78:79] offset:1024 sc1
	global_load_dwordx4 v[202:205], v192, s[78:79] offset:2048 sc1
	global_load_dwordx4 v[206:209], v192, s[78:79] offset:3072 sc1
	s_add_u32 s78, s82, 0x5000
	s_addc_u32 s79, s83, 0
	global_load_dwordx4 v[210:213], v192, s[78:79] sc1
	global_load_dwordx4 v[244:247], v192, s[78:79] offset:1024 sc1
	global_load_dwordx4 v[248:251], v192, s[78:79] offset:2048 sc1
	global_load_dwordx4 v[218:221], v192, s[78:79] offset:3072 sc1
	s_waitcnt vmcnt(16)
	v_pk_add_f32 v[0:1], v[0:1], v[64:65]
	v_pk_add_f32 v[2:3], v[2:3], v[66:67]
	v_pk_add_f32 v[4:5], v[4:5], v[72:73]
	v_pk_add_f32 v[6:7], v[6:7], v[74:75]
	v_pk_add_f32 v[8:9], v[8:9], v[88:89]
	v_pk_add_f32 v[10:11], v[10:11], v[90:91]
	v_pk_add_f32 v[12:13], v[12:13], v[96:97]
	v_pk_add_f32 v[14:15], v[14:15], v[98:99]
	v_pk_add_f32 v[16:17], v[16:17], v[108:109]
	v_pk_add_f32 v[18:19], v[18:19], v[110:111]
	v_pk_add_f32 v[20:21], v[20:21], v[116:117]
	v_pk_add_f32 v[22:23], v[22:23], v[118:119]
	v_pk_add_f32 v[24:25], v[24:25], v[128:129]
	v_pk_add_f32 v[26:27], v[26:27], v[130:131]
	v_pk_add_f32 v[28:29], v[28:29], v[140:141]
	v_pk_add_f32 v[30:31], v[30:31], v[142:143]
	s_add_u32 s78, s82, 0x6000
	s_addc_u32 s79, s83, 0
	global_load_dwordx4 v[64:67], v192, s[78:79] sc1
	global_load_dwordx4 v[72:75], v192, s[78:79] offset:1024 sc1
	global_load_dwordx4 v[88:91], v192, s[78:79] offset:2048 sc1
	global_load_dwordx4 v[96:99], v192, s[78:79] offset:3072 sc1
	s_add_u32 s78, s82, 0x7000
	s_addc_u32 s79, s83, 0
	global_load_dwordx4 v[108:111], v192, s[78:79] sc1
	global_load_dwordx4 v[116:119], v192, s[78:79] offset:1024 sc1
	global_load_dwordx4 v[128:131], v192, s[78:79] offset:2048 sc1
	global_load_dwordx4 v[140:143], v192, s[78:79] offset:3072 sc1
	s_waitcnt vmcnt(16)
	v_pk_add_f32 v[32:33], v[32:33], v[152:153]
	v_pk_add_f32 v[34:35], v[34:35], v[154:155]
	v_pk_add_f32 v[36:37], v[36:37], v[156:157]
	v_pk_add_f32 v[38:39], v[38:39], v[158:159]
	v_pk_add_f32 v[40:41], v[40:41], v[160:161]
	v_pk_add_f32 v[42:43], v[42:43], v[162:163]
	v_pk_add_f32 v[44:45], v[44:45], v[164:165]
	v_pk_add_f32 v[46:47], v[46:47], v[166:167]
	v_pk_add_f32 v[48:49], v[48:49], v[168:169]
	v_pk_add_f32 v[50:51], v[50:51], v[170:171]
	v_pk_add_f32 v[52:53], v[52:53], v[180:181]
	v_pk_add_f32 v[54:55], v[54:55], v[182:183]
	v_pk_add_f32 v[56:57], v[56:57], v[184:185]
	v_pk_add_f32 v[58:59], v[58:59], v[186:187]
	v_pk_add_f32 v[60:61], v[60:61], v[188:189]
	v_pk_add_f32 v[62:63], v[62:63], v[190:191]
	s_waitcnt vmcnt(8)
	v_pk_add_f32 v[68:69], v[68:69], v[194:195]
	v_pk_add_f32 v[70:71], v[70:71], v[196:197]
	v_pk_add_f32 v[76:77], v[76:77], v[198:199]
	v_pk_add_f32 v[78:79], v[78:79], v[200:201]
	v_pk_add_f32 v[80:81], v[80:81], v[202:203]
	v_pk_add_f32 v[82:83], v[82:83], v[204:205]
	v_pk_add_f32 v[84:85], v[84:85], v[206:207]
	v_pk_add_f32 v[86:87], v[86:87], v[208:209]
	v_pk_add_f32 v[92:93], v[92:93], v[210:211]
	v_pk_add_f32 v[94:95], v[94:95], v[212:213]
	v_pk_add_f32 v[100:101], v[100:101], v[244:245]
	v_pk_add_f32 v[102:103], v[102:103], v[246:247]
	v_pk_add_f32 v[104:105], v[104:105], v[248:249]
	v_pk_add_f32 v[106:107], v[106:107], v[250:251]
	v_pk_add_f32 v[112:113], v[112:113], v[218:219]
	v_pk_add_f32 v[114:115], v[114:115], v[220:221]
	s_waitcnt vmcnt(0)
	v_pk_add_f32 v[120:121], v[120:121], v[64:65]
	v_pk_add_f32 v[122:123], v[122:123], v[66:67]
	v_pk_add_f32 v[124:125], v[124:125], v[72:73]
	v_pk_add_f32 v[126:127], v[126:127], v[74:75]
	v_pk_add_f32 v[132:133], v[132:133], v[88:89]
	v_pk_add_f32 v[134:135], v[134:135], v[90:91]
	v_pk_add_f32 v[136:137], v[136:137], v[96:97]
	v_pk_add_f32 v[138:139], v[138:139], v[98:99]
	v_pk_add_f32 v[144:145], v[144:145], v[108:109]
	v_pk_add_f32 v[146:147], v[146:147], v[110:111]
	v_pk_add_f32 v[148:149], v[148:149], v[116:117]
	v_pk_add_f32 v[150:151], v[150:151], v[118:119]
	v_pk_add_f32 v[172:173], v[172:173], v[128:129]
	v_pk_add_f32 v[174:175], v[174:175], v[130:131]
	v_pk_add_f32 v[176:177], v[176:177], v[140:141]
	v_pk_add_f32 v[178:179], v[178:179], v[142:143]
